# Hyena queue items run at priority 3 (equal to the SSD blocks) so the barrier-synchronised K-loop waves are not starved
# speedup vs baseline: 1.0034x; 1.0034x over previous
; DI int TID() { int t = threadIdx.x; asm volatile("" : "+v"(t)); return t; }
; DI void hyena_item(const Params& p, int l, int it) {
;     ...
;   if (it < 2048) { c = it >> 3; f = l; L = 2048; posoff = CTXL; tt0 = (it & 7) * 256 + w * 64; ntile = 32; }
;   else { c = it - 2048; f = 2; L = 256; posoff = 0; tt0 = w * 64; ntile = 4; }
;   const u16* R0 = WSP(const u16, OFF_RF) + ((size_t)(f * 256 + c) * 2) * RSTR;
;   const u16* R1 = R0 + RSTR;
;   const u16* UT = WSP(const u16, OFF_UT);
;   const int l16 = lane & 15, kg = lane >> 4;
;   f32x4 acc[4];
; #pragma unroll
;   for (int i = 0; i < 4; ++i) acc[i] = (f32x4){0.f, 0.f, 0.f, 0.f};
;   const u16* ub = UT + ((size_t)(c * 16 + l16)) * TPB + posoff + kg * 8;
;   const u16* rsel = (l16 & 1) ? (R1 - 1) : R0;
;   const int nb = L - (tt0 + l16) + kg * 8;
;   for (int s0 = 0; s0 < L; s0 += 32) {
;     const bf16x8 bfrag = *(const bf16x8*)(ub + s0);
; #pragma unroll
;     for (int i = 0; i < 4; ++i) {
;       const u32* ap = (const u32*)(rsel + (nb - 16 * i + s0));
;       union { u32 u[4]; bf16x8 v; } au;
;       au.u[0] = ap[0]; au.u[1] = ap[1]; au.u[2] = ap[2]; au.u[3] = ap[3];
;       acc[i] = __builtin_amdgcn_mfma_f32_16x16x32_bf16(au.v, bfrag, acc[i], 0, 0, 0);
;     }
;   }
;     ...
;     if (TID() == 0) *sitem = atomicAdd(ctr, 1);
;     __syncthreads();
;     const int it = *sitem;
;     __syncthreads();
;     if (it >= nf + nh) break;
;     if (it < nf) fnet_item(p, it, smem);
;     else if (it - nf < 1024) hyena_item_lat(p, l, it - nf);
;     else hyena_item(p, l, it - nf + 1024);
.LBB0_1133:
	s_or_b64 exec, exec, s[34:35]
	v_readlane_b32 s13, v254, 1
	s_waitcnt lgkmcnt(0)
	s_barrier
	v_mov_b32_e32 v0, s13
	ds_read_b32 v0, v0
	s_mov_b64 s[34:35], -1
	s_waitcnt lgkmcnt(0)
	s_barrier
	v_cmp_le_i32_e32 vcc, s41, v0
	v_readfirstlane_b32 s45, v0
	s_cbranch_vccnz .LBB0_1128
	s_cmp_ge_i32 s45, s40
	s_cbranch_scc0 .LBB0_1142
	s_sub_i32 s13, s45, s40
	s_cmpk_gt_i32 s13, 0x3ff
	s_cbranch_scc0 .LBB0_1137
	s_setprio 3
	v_and_b32_e32 v17, 15, v218
	v_and_b32_e32 v16, 0xffffffc0, v218
	v_bfe_u32 v22, v218, 4, 2
	s_add_i32 s36, s13, 0xfffffc00
	s_add_i32 s38, s13, 0x400
	v_lshl_or_b32 v1, s36, 4, v17
	s_movk_i32 s16, 0x900
	s_mul_i32 s86, s38, 0x2020
	v_mul_lo_u32 v172, v1, s16
	v_readlane_b32 s16, v255, 50
	s_lshl_b64 s[34:35], s[86:87], 1
	v_readlane_b32 s17, v255, 51
	s_add_u32 s34, s96, s34
	s_addc_u32 s35, s97, s35
	s_nop 2
	v_lshl_add_u64 v[18:19], v[172:173], 1, s[16:17]
	v_lshlrev_b32_e32 v172, 4, v22
	v_lshl_add_u64 v[2:3], v[18:19], 0, v[172:173]
	v_bfe_i32 v0, v218, 0, 1
	v_and_b32_e32 v172, 0x201e, v0
	v_lshl_add_u64 v[0:1], s[34:35], 0, v[172:173]
	s_mov_b64 s[34:35], 0x199c8000
	v_lshl_add_u64 v[0:1], v[0:1], 0, s[34:35]
	v_lshlrev_b32_e32 v4, 3, v22
	v_sub_u32_e32 v4, v4, v16
	v_add_u32_e32 v4, 0x100, v4
	v_sub_u32_e32 v6, v4, v17
	v_ashrrev_i32_e32 v7, 31, v6
	v_lshl_add_u64 v[6:7], v[6:7], 1, v[0:1]
	global_load_dwordx4 v[32:35], v[6:7], off offset:-96
	global_load_dwordx4 v[36:39], v[6:7], off offset:-64
	global_load_dwordx4 v[40:43], v[6:7], off offset:-32
	global_load_dwordx4 v[44:47], v[6:7], off
	global_load_dwordx4 v[48:51], v[6:7], off offset:32
	global_load_dwordx4 v[52:55], v[6:7], off offset:64
	global_load_dwordx4 v[56:59], v[6:7], off offset:96
	global_load_dwordx4 v[60:63], v[6:7], off offset:128
	global_load_dwordx4 v[64:67], v[6:7], off offset:160
	global_load_dwordx4 v[68:71], v[6:7], off offset:192
	global_load_dwordx4 v[72:75], v[6:7], off offset:224
	global_load_dwordx4 v[76:79], v[6:7], off offset:256
	global_load_dwordx4 v[80:83], v[6:7], off offset:288
	global_load_dwordx4 v[84:87], v[6:7], off offset:320
	global_load_dwordx4 v[88:91], v[6:7], off offset:352
	global_load_dwordx4 v[92:95], v[6:7], off offset:384
	global_load_dwordx4 v[96:99], v[6:7], off offset:416
	global_load_dwordx4 v[100:103], v[6:7], off offset:448
	global_load_dwordx4 v[104:107], v[2:3], off
	global_load_dwordx4 v[108:111], v[2:3], off offset:64
	global_load_dwordx4 v[112:115], v[2:3], off offset:128
	global_load_dwordx4 v[116:119], v[2:3], off offset:192
	global_load_dwordx4 v[120:123], v[2:3], off offset:256
	global_load_dwordx4 v[124:127], v[2:3], off offset:320
	global_load_dwordx4 v[128:131], v[2:3], off offset:384
	global_load_dwordx4 v[132:135], v[2:3], off offset:448
	s_mov_b32 s39, s87
	s_lshl_b64 s[34:35], s[38:39], 2
	v_readlane_b32 s16, v254, 45
	v_readlane_b32 s17, v254, 46
	s_add_u32 s34, s16, s34
	s_addc_u32 s35, s17, s35
	v_mov_b32_e32 v149, 0xe000
	global_load_dword v144, v149, s[34:35]
	global_load_dword v145, v149, s[34:35] offset:1024
	global_load_dword v146, v149, s[34:35] offset:2048
	global_load_dword v147, v149, s[34:35] offset:3072
	s_add_i32 s86, s36, s42
	s_lshl_b64 s[34:35], s[86:87], 2
	v_readlane_b32 s18, v254, 31
	v_readlane_b32 s19, v254, 32
	s_add_u32 s34, s18, s34
	s_addc_u32 s35, s19, s35
	global_load_dword v148, v173, s[34:35]
	v_lshl_add_u32 v25, v22, 2, v16
	v_mov_b32_e32 v27, 0
	v_lshlrev_b32_e32 v26, 1, v25
	v_lshl_add_u64 v[28:29], v[18:19], 0, v[26:27]
	global_load_dwordx2 v[136:137], v[28:29], off
	global_load_dwordx2 v[138:139], v[28:29], off offset:32
	global_load_dwordx2 v[140:141], v[28:29], off offset:64
	global_load_dwordx2 v[142:143], v[28:29], off offset:96
	v_mov_b64_e32 v[0:1], 0
	v_mov_b64_e32 v[2:3], 0
	v_mov_b64_e32 v[4:5], 0
	v_mov_b64_e32 v[6:7], 0
	v_mov_b64_e32 v[8:9], 0
	v_mov_b64_e32 v[10:11], 0
	v_mov_b64_e32 v[12:13], 0
	v_mov_b64_e32 v[14:15], 0
	v_lshlrev_b32_e32 v30, 10, v17
	v_lshl_add_u32 v30, v25, 2, v30
	s_lshl_b32 s16, s36, 14
	s_add_u32 s16, s16, 0x2000000
	s_add_u32 s16, s96, s16
	s_addc_u32 s17, s97, 0
	s_waitcnt vmcnt(16)
	v_mfma_f32_16x16x32_bf16 v[0:3], v[44:47], v[104:107], v[0:3]
	v_mfma_f32_16x16x32_bf16 v[4:7], v[40:43], v[104:107], v[4:7]
	v_mfma_f32_16x16x32_bf16 v[8:11], v[36:39], v[104:107], v[8:11]
	v_mfma_f32_16x16x32_bf16 v[12:15], v[32:35], v[104:107], v[12:15]
	s_waitcnt vmcnt(15)
	v_mfma_f32_16x16x32_bf16 v[0:3], v[52:55], v[108:111], v[0:3]
	v_mfma_f32_16x16x32_bf16 v[4:7], v[48:51], v[108:111], v[4:7]
	v_mfma_f32_16x16x32_bf16 v[8:11], v[44:47], v[108:111], v[8:11]
	v_mfma_f32_16x16x32_bf16 v[12:15], v[40:43], v[108:111], v[12:15]
	s_waitcnt vmcnt(14)
	v_mfma_f32_16x16x32_bf16 v[0:3], v[60:63], v[112:115], v[0:3]
	v_mfma_f32_16x16x32_bf16 v[4:7], v[56:59], v[112:115], v[4:7]
	v_mfma_f32_16x16x32_bf16 v[8:11], v[52:55], v[112:115], v[8:11]
	v_mfma_f32_16x16x32_bf16 v[12:15], v[48:51], v[112:115], v[12:15]
	s_waitcnt vmcnt(13)
	v_mfma_f32_16x16x32_bf16 v[0:3], v[68:71], v[116:119], v[0:3]
	v_mfma_f32_16x16x32_bf16 v[4:7], v[64:67], v[116:119], v[4:7]
	v_mfma_f32_16x16x32_bf16 v[8:11], v[60:63], v[116:119], v[8:11]
	v_mfma_f32_16x16x32_bf16 v[12:15], v[56:59], v[116:119], v[12:15]
	s_waitcnt vmcnt(12)
	v_mfma_f32_16x16x32_bf16 v[0:3], v[76:79], v[120:123], v[0:3]
	v_mfma_f32_16x16x32_bf16 v[4:7], v[72:75], v[120:123], v[4:7]
	v_mfma_f32_16x16x32_bf16 v[8:11], v[68:71], v[120:123], v[8:11]
	v_mfma_f32_16x16x32_bf16 v[12:15], v[64:67], v[120:123], v[12:15]
	s_waitcnt vmcnt(11)
	v_mfma_f32_16x16x32_bf16 v[0:3], v[84:87], v[124:127], v[0:3]
	v_mfma_f32_16x16x32_bf16 v[4:7], v[80:83], v[124:127], v[4:7]
	v_mfma_f32_16x16x32_bf16 v[8:11], v[76:79], v[124:127], v[8:11]
	v_mfma_f32_16x16x32_bf16 v[12:15], v[72:75], v[124:127], v[12:15]
	s_waitcnt vmcnt(10)
; DI u16 f2bf(float x) { u32 u = __float_as_uint(x); u += 0x7fffu + ((u >> 16) & 1u); return (u16)(u >> 16); }
; DI float bf2f(u16 v) { return __uint_as_float(((u32)v) << 16); }
; DI void hyena_item(const Params& p, int l, int it) {
;     ...
;   for (int s0 = 0; s0 < L; s0 += 32) {
;     const bf16x8 bfrag = *(const bf16x8*)(ub + s0);
; #pragma unroll
;     for (int i = 0; i < 4; ++i) {
;       const u32* ap = (const u32*)(rsel + (nb - 16 * i + s0));
;       union { u32 u[4]; bf16x8 v; } au;
;       au.u[0] = ap[0]; au.u[1] = ap[1]; au.u[2] = ap[2]; au.u[3] = ap[3];
;       acc[i] = __builtin_amdgcn_mfma_f32_16x16x32_bf16(au.v, bfrag, acc[i], 0, 0, 0);
;     }
;   }
;   float ssq = 0.f;
;   for (int t = 0; t < ntile; ++t) ssq += WSP(const float, OFF_PART)[(size_t)(f * 32 + t) * 256 + c];
;   const float scale = rsqrtf(ssq + EPSF);
;   const float bias = p.in[I_HYBIAS][l * 256 + c];
;   const u16* X1C = WSP(const u16, OFF_X1C);
;   u16* YM = WSP(u16, OFF_ACT);
;   const int b = l16;
; #pragma unroll
;   for (int i = 0; i < 4; ++i)
; #pragma unroll
;     for (int r = 0; r < 4; ++r) {
;       const int t = tt0 + 16 * i + kg * 4 + r;
;       const size_t row = (size_t)b * TPB + posoff + t;
;       const float u = bf2f(UT[((size_t)(c * 16 + b)) * TPB + posoff + t]);
;       const float x1 = bf2f(X1C[row * 256 + c]);
;       YM[row * 1024 + c] = f2bf(x1 * (scale * acc[i][r] + bias * u));
; DI void hyena_item_lat(const Params& p, int l, int it) {
;     ...
;   const int c = it >> 2, f = l, L = 2048, posoff = CTXL;
;   const int tt0 = (it & 3) * 512 + w * 128;
;   const u16* R0 = WSP(const u16, OFF_RF) + ((size_t)(f * 256 + c) * 2) * RSTR;
;   const u16* R1 = R0 + RSTR;
;   const u16* UT = WSP(const u16, OFF_UT);
;   const int l16 = lane & 15, kg = lane >> 4;
;   f32x4 acc[8];
; #pragma unroll
;   for (int i = 0; i < 8; ++i) acc[i] = (f32x4){0.f, 0.f, 0.f, 0.f};
;   const u16* ub = UT + ((size_t)(c * 16 + l16)) * TPB + posoff + kg * 8;
;   const u16* rsel = (l16 & 1) ? (R1 - 1) : R0;
;   const int nb = L - (tt0 + l16) + kg * 8;
;   union AF { u32 u[4]; bf16x8 v; };
;   AF a[8];
;     ...
; #pragma unroll
;   for (int i = 2; i < 8; ++i) HY_LOADA(a[i], nb - 16 * i)
	v_mfma_f32_16x16x32_bf16 v[0:3], v[92:95], v[128:131], v[0:3]
	v_mfma_f32_16x16x32_bf16 v[4:7], v[88:91], v[128:131], v[4:7]
	v_mfma_f32_16x16x32_bf16 v[8:11], v[84:87], v[128:131], v[8:11]
	v_mfma_f32_16x16x32_bf16 v[12:15], v[80:83], v[128:131], v[12:15]
	s_waitcnt vmcnt(9)
	v_mfma_f32_16x16x32_bf16 v[0:3], v[100:103], v[132:135], v[0:3]
	v_mfma_f32_16x16x32_bf16 v[4:7], v[96:99], v[132:135], v[4:7]
	v_mfma_f32_16x16x32_bf16 v[8:11], v[92:95], v[132:135], v[8:11]
	v_mfma_f32_16x16x32_bf16 v[12:15], v[88:91], v[132:135], v[12:15]
	s_waitcnt vmcnt(0)
	v_add_f32_e32 v20, 0, v144
	v_add_f32_e32 v20, v20, v145
	v_add_f32_e32 v20, v20, v146
	v_add_f32_e32 v20, v20, v147
	s_mov_b32 s18, 0x800000
	v_add_f32_e32 v20, 0x358637bd, v20
	v_cmp_gt_f32_e32 vcc, s18, v20
	v_mul_f32_e32 v21, 0x4b800000, v20
	s_nop 1
	v_cndmask_b32_e32 v20, v20, v21, vcc
	v_rsq_f32_e32 v20, v20
	s_nop 0
	v_mul_f32_e32 v21, 0x45800000, v20
	v_cndmask_b32_e32 v20, v20, v21, vcc
	s_nop 4
	v_lshlrev_b32_e32 v21, 16, v136
	v_mul_f32_e32 v21, v148, v21
	v_fmac_f32_e32 v21, v0, v20
	v_mov_b32_e32 v0, v21
	v_and_b32_e32 v21, 0xffff0000, v136
	v_mul_f32_e32 v21, v148, v21
	v_fmac_f32_e32 v21, v1, v20
	v_mov_b32_e32 v1, v21
	v_lshlrev_b32_e32 v21, 16, v137
	v_mul_f32_e32 v21, v148, v21
	v_fmac_f32_e32 v21, v2, v20
	v_mov_b32_e32 v2, v21
	v_and_b32_e32 v21, 0xffff0000, v137
	v_mul_f32_e32 v21, v148, v21
	v_fmac_f32_e32 v21, v3, v20
	v_mov_b32_e32 v3, v21
	v_lshlrev_b32_e32 v21, 16, v138
	v_mul_f32_e32 v21, v148, v21
	v_fmac_f32_e32 v21, v4, v20
	v_mov_b32_e32 v4, v21
	v_and_b32_e32 v21, 0xffff0000, v138
	v_mul_f32_e32 v21, v148, v21
	v_fmac_f32_e32 v21, v5, v20
	v_mov_b32_e32 v5, v21
	v_lshlrev_b32_e32 v21, 16, v139
	v_mul_f32_e32 v21, v148, v21
	v_fmac_f32_e32 v21, v6, v20
	v_mov_b32_e32 v6, v21
	v_and_b32_e32 v21, 0xffff0000, v139
	v_mul_f32_e32 v21, v148, v21
	v_fmac_f32_e32 v21, v7, v20
	v_mov_b32_e32 v7, v21
	v_lshlrev_b32_e32 v21, 16, v140
	v_mul_f32_e32 v21, v148, v21
	v_fmac_f32_e32 v21, v8, v20
	v_mov_b32_e32 v8, v21
	v_and_b32_e32 v21, 0xffff0000, v140
	v_mul_f32_e32 v21, v148, v21
	v_fmac_f32_e32 v21, v9, v20
	v_mov_b32_e32 v9, v21
	v_lshlrev_b32_e32 v21, 16, v141
	v_mul_f32_e32 v21, v148, v21
	v_fmac_f32_e32 v21, v10, v20
	v_mov_b32_e32 v10, v21
	v_and_b32_e32 v21, 0xffff0000, v141
	v_mul_f32_e32 v21, v148, v21
	v_fmac_f32_e32 v21, v11, v20
	v_mov_b32_e32 v11, v21
	v_lshlrev_b32_e32 v21, 16, v142
	v_mul_f32_e32 v21, v148, v21
	v_fmac_f32_e32 v21, v12, v20
	v_mov_b32_e32 v12, v21
	v_and_b32_e32 v21, 0xffff0000, v142
	v_mul_f32_e32 v21, v148, v21
	v_fmac_f32_e32 v21, v13, v20
	v_mov_b32_e32 v13, v21
	v_lshlrev_b32_e32 v21, 16, v143
	v_mul_f32_e32 v21, v148, v21
	v_fmac_f32_e32 v21, v14, v20
	v_mov_b32_e32 v14, v21
	v_and_b32_e32 v21, 0xffff0000, v143
	v_mul_f32_e32 v21, v148, v21
	v_fmac_f32_e32 v21, v15, v20
	v_mov_b32_e32 v15, v21
	global_store_dwordx4 v30, v[0:3], s[16:17]
	global_store_dwordx4 v30, v[4:7], s[16:17] offset:64
	global_store_dwordx4 v30, v[8:11], s[16:17] offset:128
	global_store_dwordx4 v30, v[12:15], s[16:17] offset:192
	s_mov_b32 s24, s64
	v_readlane_b32 s18, v254, 10
	v_readlane_b32 s19, v254, 11
	s_mov_b64 s[34:35], 0
.LBB0_1137:
	s_andn2_b64 vcc, exec, s[34:35]
	s_cbranch_vccnz .LBB0_1141
	s_setprio 3
	s_ashr_i32 s34, s13, 2
	v_mov_b32_e32 v0, v218
	v_mov_b32_e32 v1, v218
	s_add_i32 s36, s34, s42
	s_lshl_b32 s13, s13, 9
	s_ashr_i32 s37, s36, 31
	s_mul_i32 s38, s36, 0x4040
	v_readlane_b32 s16, v254, 47
	v_lshlrev_b32_e32 v1, 1, v1
	s_mul_hi_i32 s35, s36, 0x4040
	v_readlane_b32 s17, v254, 48
	s_add_u32 s38, s16, s38
	v_and_b32_e32 v1, 0xffffff80, v1
	s_addc_u32 s39, s17, s35
	s_and_b32 s13, s13, 0x600
	v_add_u32_e32 v63, s13, v1
	v_and_b32_e32 v62, 15, v0
	v_bfe_u32 v64, v0, 4, 2
	v_bfe_i32 v0, v0, 0, 1
	v_lshlrev_b32_e32 v1, 3, v64
	v_and_b32_e32 v172, 0x201e, v0
	v_or_b32_e32 v0, v63, v62
	v_sub_u32_e32 v58, v1, v0
	v_lshl_add_u64 v[56:57], s[38:39], 0, v[172:173]
	v_ashrrev_i32_e32 v59, 31, v58
	v_lshl_add_u64 v[0:1], v[58:59], 1, v[56:57]
	global_load_dwordx4 v[40:43], v[0:1], off offset:4032
	global_load_dwordx4 v[44:47], v[0:1], off offset:4000
	global_load_dwordx4 v[32:35], v[0:1], off offset:3968
	global_load_dwordx4 v[36:39], v[0:1], off offset:3936
	global_load_dwordx4 v[48:51], v[0:1], off offset:3904
	global_load_dwordx4 v[52:55], v[0:1], off offset:3872
	s_lshl_b32 s35, s34, 4
	v_or_b32_e32 v59, s35, v62
	v_mad_i64_i32 v[0:1], s[38:39], v59, s9, 0
	v_readlane_b32 s16, v255, 56
	v_lshl_or_b32 v0, v64, 4, v0
	v_readlane_b32 s17, v255, 57
	v_mov_b32_e32 v28, 0
	s_mov_b64 s[46:47], s[20:21]
	s_movk_i32 s13, 0xff80
	v_lshl_add_u64 v[60:61], s[16:17], 0, v[0:1]
	v_mov_b32_e32 v29, v28
	v_mov_b32_e32 v30, v28
	v_mov_b32_e32 v31, v28
	v_mov_b32_e32 v24, v28
	v_mov_b32_e32 v25, v28
	v_mov_b32_e32 v26, v28
	v_mov_b32_e32 v27, v28
	v_mov_b32_e32 v20, v28
	v_mov_b32_e32 v21, v28
	v_mov_b32_e32 v22, v28
	v_mov_b32_e32 v23, v28
	v_mov_b32_e32 v16, v28
	v_mov_b32_e32 v17, v28
	v_mov_b32_e32 v18, v28
	v_mov_b32_e32 v19, v28
	v_mov_b32_e32 v12, v28
	v_mov_b32_e32 v13, v28
	v_mov_b32_e32 v14, v28
	v_mov_b32_e32 v15, v28
	v_mov_b32_e32 v8, v28
	v_mov_b32_e32 v9, v28
	v_mov_b32_e32 v10, v28
	v_mov_b32_e32 v11, v28
	v_mov_b32_e32 v4, v28
	v_mov_b32_e32 v5, v28
	v_mov_b32_e32 v6, v28
	v_mov_b32_e32 v7, v28
	v_mov_b32_e32 v0, v28
	v_mov_b32_e32 v1, v28
	v_mov_b32_e32 v2, v28
	v_mov_b32_e32 v3, v28
	v_and_b32_e32 v92, 0xc0, v218
	v_mov_b32_e32 v93, 0
	v_lshlrev_b32_e32 v94, 4, v218
	v_and_b32_e32 v95, 63, v218
	v_lshl_add_u64 v[90:91], v[92:93], 0, v[60:61]
	v_lshlrev_b32_e32 v95, 4, v95
	global_load_dwordx4 v[82:85], v[90:91], off offset:-192

;     ...
;     if (it < nf) fnet_item(p, it, smem);
;     else if (it - nf < 1024) hyena_item_lat(p, l, it - nf);
;     else hyena_item(p, l, it - nf + 1024);
.LBB0_1141:
	s_setprio 0
	s_mov_b64 s[34:35], 0
